# residual-GEMM pre-loop: the two serialized column-constant loads batched behind one wait; on v32
# baseline (speedup 1.0000x reference)
.LBB0_780:
	s_ashr_i32 s0, s3, 3
	s_add_i32 s0, s15, s0
	s_ashr_i32 s1, s0, 31
	s_lshr_b32 s1, s1, 28
	s_add_i32 s1, s0, s1
	s_and_b32 s1, s1, 0xfff0
	s_sub_i32 s0, s0, s1
	s_bfe_i32 s1, s0, 0x80000
	s_bfe_u32 s1, s1, 0x2000d
	s_add_i32 s0, s0, s1
	s_bfe_i32 s0, s0, 0x80000
	s_sext_i32_i16 s0, s0
	s_ashr_i32 s0, s0, 2
	v_mov_b32_e32 v3, 0x6050400
	s_waitcnt vmcnt(0) lgkmcnt(0)
	v_perm_b32 v4, s0, v2, v3
	s_movk_i32 s0, 0x100
	v_cmp_gt_i32_e32 vcc, s0, v2
	v_mov_b32_e32 v3, s9
	v_mov_b32_e32 v5, s7
	v_cndmask_b32_e32 v7, v3, v5, vcc
	v_mov_b32_e32 v3, s8
	v_mov_b32_e32 v5, s6
	v_cndmask_b32_e32 v6, v3, v5, vcc
	v_ashrrev_i32_e32 v5, 31, v4
	v_lshlrev_b64 v[4:5], 2, v[4:5]
	v_lshl_add_u64 v[6:7], v[6:7], 0, v[4:5]
	global_load_dword v3, v[6:7], off
	v_lshl_add_u32 v6, v2, 2, 0
	v_readlane_b32 s14, v254, 59
	v_readlane_b32 s0, v254, 57
	v_add_u32_e32 v8, 0x20400, v6
	v_readlane_b32 s15, v254, 60
	v_readlane_b32 s1, v254, 58
	s_nop 1
	v_mov_b32_e32 v9, s15
	v_mov_b32_e32 v6, s1
	v_cndmask_b32_e32 v7, v9, v6, vcc
	v_mov_b32_e32 v9, s14
	v_mov_b32_e32 v6, s0
	v_cndmask_b32_e32 v6, v9, v6, vcc
	v_lshl_add_u64 v[4:5], v[6:7], 0, v[4:5]
	v_add_co_u32_e32 v4, vcc, 0x5000, v4
	s_nop 1
	v_addc_co_u32_e32 v5, vcc, 0, v5, vcc
	global_load_dword v9, v[4:5], off
	s_waitcnt vmcnt(0) lgkmcnt(0)
	ds_write_b32 v8, v3
	ds_write_b32 v8, v9 offset:2048
